# attention unit epilogue: norm gains prefetched at loop exit into dead score registers and reused for the second pass; the 16 serialized LDS read+FMA steps of the differential combine issued as batched
# speedup vs baseline: 1.0025x; 1.0025x over previous
; #define LAS __attribute__((address_space(3)))
; __device__ __forceinline__ int crow(int r, int hi) { return (r & 3) + 8 * (r >> 2) + 4 * hi; }
; template <int VAR>
; __device__ __forceinline__ void attn_unit(const Args& a, int l, int b, int h, int qrow0  , bool ctxu, const bf16* Z, bf16* Y, LAS unsigned char* lds) {
;     ...
;     for (int t = 0; t < NT; t += 2) {
;         __syncthreads();
;         if (t + 2 < NT) AT_LOAD(ka0, ka1, va0, va1, t + 2);
;         attn_tile(Kb0, vb0, q0, q1, negm, m, o0, o1, lacc, t == 0, wsf, r32, hi);
;         AT_STORE(kb0, kb1, vb0_, vb1_, 1);
;         __syncthreads();
;         if (t + 3 < NT) AT_LOAD(kb0, kb1, vb0_, vb1_, t + 3);
;         attn_tile(Kb0 + AT_KB, vb0 + AT_VB, q0, q1, negm, m, o0, o1, lacc, false, wsf, r32, hi);
;         if (t + 2 < NT) AT_STORE(ka0, ka1, va0, va1, 0);
;     }
;     ...
;     float lam, omli;
;     { float s1 = 0.f, s2 = 0.f;
;       for (int i = 0; i < 32; ++i) { s1 += a.lam_q1[l * 32 + i] * a.lam_k1[l * 32 + i]; s2 += a.lam_q2[l * 32 + i] * a.lam_k2[l * 32 + i]; }
;       const float li = 0.8f - 0.6f * expf(-0.3f * (float)l); lam = expf(s1) - expf(s2) + li; omli = 1.f - li; }
;     LAS float* stg = (LAS float*)(lds + AT_ST) + wq * 2048;
;     if (comp == 1) {
; #pragma unroll
;         for (int r = 0; r < 16; ++r) { const int qr = crow(r, hi); const float il = lam * __builtin_amdgcn_rcpf(lacc[r]); stg[qr * 64 + r32] = o0[r] * il; stg[qr * 64 + 32 + r32] = o1[r] * il; }
;     }
;     __syncthreads();
;     if (comp == 0) {
; #pragma unroll
;         for (int r = 0; r < 16; ++r) { const int qr = crow(r, hi); const float il = __builtin_amdgcn_rcpf(lacc[r]); o0[r] = o0[r] * il - stg[qr * 64 + r32]; o1[r] = o1[r] * il - stg[qr * 64 + 32 + r32]; }
;         asm volatile("s_waitcnt lgkmcnt(0)" ::: "memory");
; #pragma unroll
;         for (int r = 0; r < 16; ++r) { const int qr = crow(r, hi); stg[qr * 64 + r32] = o0[r]; stg[qr * 64 + 32 + r32] = o1[r]; }
;         asm volatile("s_waitcnt lgkmcnt(0)" ::: "memory");
;         const int ch = lane & 7;
;         float gsub[8];
; #pragma unroll
;         for (int i = 0; i < 8; ++i) gsub[i] = a.subln_g[l * 64 + ch * 8 + i] * omli;
.Lat_ndF5:
	ds_read_b128 v[48:51], v144 offset:0
	ds_read_b128 v[52:55], v145 offset:0
	ds_read_b128 v[56:59], v144 offset:4096
	ds_read_b128 v[60:63], v145 offset:4096
	v_mfma_f32_32x32x16_bf16 v[80:95], v[162:165], v[192:195], v[80:95]
	v_mfma_f32_32x32x16_bf16 v[200:215], v[162:165], v[196:199], v[200:215]
	s_add_u32 s33, s33, 1
	s_cmp_lt_u32 s33, 22
	s_cbranch_scc1 .Lat_floop
	v_add_f32_e32 v132, v128, v129
	v_mov_b32_e32 v133, v132
	s_nop 1
	v_permlane32_swap_b32_e32 v132, v133
	v_add_f32_e32 v135, v132, v133
	v_add_f32_e32 v132, v130, v131
	v_mov_b32_e32 v133, v132
	s_nop 1
	v_permlane32_swap_b32_e32 v132, v133
	v_add_f32_e32 v130, v132, v133
	s_nop 7
	s_nop 7
	v_add_f32_e32 v132, v135, v130
	v_mov_b32_e32 v133, 0
	v_add_f32_e64 v132, v132, |v0|
	v_add_f32_e64 v133, v133, |v1|
	v_add_f32_e64 v132, v132, |v2|
	v_add_f32_e64 v133, v133, |v3|
	v_add_f32_e64 v132, v132, |v4|
	v_add_f32_e64 v133, v133, |v5|
	v_add_f32_e64 v132, v132, |v6|
	v_add_f32_e64 v133, v133, |v7|
	v_add_f32_e64 v132, v132, |v8|
	v_add_f32_e64 v133, v133, |v9|
	v_add_f32_e64 v132, v132, |v10|
	v_add_f32_e64 v133, v133, |v11|
	v_add_f32_e64 v132, v132, |v12|
	v_add_f32_e64 v133, v133, |v13|
	v_add_f32_e64 v132, v132, |v14|
	v_add_f32_e64 v133, v133, |v15|
	v_add_f32_e64 v132, v132, |v16|
	v_add_f32_e64 v133, v133, |v17|
	v_add_f32_e64 v132, v132, |v18|
	v_add_f32_e64 v133, v133, |v19|
	v_add_f32_e64 v132, v132, |v20|
	v_add_f32_e64 v133, v133, |v21|
	v_add_f32_e64 v132, v132, |v22|
	v_add_f32_e64 v133, v133, |v23|
	v_add_f32_e64 v132, v132, |v24|
	v_add_f32_e64 v133, v133, |v25|
	v_add_f32_e64 v132, v132, |v26|
	v_add_f32_e64 v133, v133, |v27|
	v_add_f32_e64 v132, v132, |v28|
	v_add_f32_e64 v133, v133, |v29|
	v_add_f32_e64 v132, v132, |v30|
	v_add_f32_e64 v133, v133, |v31|
	v_add_f32_e64 v132, v132, |v80|
	v_add_f32_e64 v133, v133, |v81|
	v_add_f32_e64 v132, v132, |v82|
	v_add_f32_e64 v133, v133, |v83|
	v_add_f32_e64 v132, v132, |v84|
	v_add_f32_e64 v133, v133, |v85|
	v_add_f32_e64 v132, v132, |v86|
	v_add_f32_e64 v133, v133, |v87|
	v_add_f32_e64 v132, v132, |v88|
	v_add_f32_e64 v133, v133, |v89|
	v_add_f32_e64 v132, v132, |v90|
	v_add_f32_e64 v133, v133, |v91|
	v_add_f32_e64 v132, v132, |v92|
	v_add_f32_e64 v133, v133, |v93|
	v_add_f32_e64 v132, v132, |v94|
	v_add_f32_e64 v133, v133, |v95|
	v_add_f32_e64 v132, v132, |v200|
	v_add_f32_e64 v133, v133, |v201|
	v_add_f32_e64 v132, v132, |v202|
	v_add_f32_e64 v133, v133, |v203|
	v_add_f32_e64 v132, v132, |v204|
	v_add_f32_e64 v133, v133, |v205|
	v_add_f32_e64 v132, v132, |v206|
	v_add_f32_e64 v133, v133, |v207|
	v_add_f32_e64 v132, v132, |v208|
	v_add_f32_e64 v133, v133, |v209|
	v_add_f32_e64 v132, v132, |v210|
	v_add_f32_e64 v133, v133, |v211|
	v_add_f32_e64 v132, v132, |v212|
	v_add_f32_e64 v133, v133, |v213|
	v_add_f32_e64 v132, v132, |v214|
	v_add_f32_e64 v133, v133, |v215|
	v_add_f32_e32 v132, v132, v133
	v_mov_b32_e32 v133, 0x76800000
	v_cmp_nlt_f32_e32 vcc, v132, v133
	s_cmp_lg_u64 vcc, 0
	s_cselect_b32 s50, 1, 0
	v_mov_b32_e32 v134, 0x19880
	v_mov_b32_e32 v133, s50
	ds_or_b32 v134, v133
	s_waitcnt lgkmcnt(0)
	s_barrier
	ds_read_b32 v133, v134
	s_waitcnt lgkmcnt(0)
	v_readfirstlane_b32 s50, v133
	s_cmp_lg_u32 s50, 0
	s_cbranch_scc1 .Lat_safe_entry
	s_nop 7
	s_waitcnt lgkmcnt(0)
	ds_write_b32 v148, v135
	s_waitcnt lgkmcnt(0)
	ds_read_b128 v[32:35], v147 offset:0
	ds_read_b128 v[36:39], v147 offset:32
	ds_read_b128 v[40:43], v147 offset:64
	ds_read_b128 v[44:47], v147 offset:96
	s_waitcnt lgkmcnt(0)
	s_mov_b32 s93, 0
	s_waitcnt vmcnt(0)
	v_or_b32_e32 v132, s58, v228
	v_mov_b32_e32 v133, 0
	v_lshl_add_u64 v[132:133], v[132:133], 2, s[78:79]
	global_load_dwordx4 v[100:103], v[132:133], off offset:16
	global_load_dwordx4 v[96:99], v[132:133], off
	s_setprio 0
	s_branch .LBB0_459

; #define LAS __attribute__((address_space(3)))
; __device__ __forceinline__ int crow(int r, int hi) { return (r & 3) + 8 * (r >> 2) + 4 * hi; }
; template <int VAR>
; __device__ __forceinline__ void attn_unit(const Args& a, int l, int b, int h, int qrow0  , bool ctxu, const bf16* Z, bf16* Y, LAS unsigned char* lds) {
;     ...
;     for (int t = 0; t < NT; t += 2) {
;         __syncthreads();
;         if (t + 2 < NT) AT_LOAD(ka0, ka1, va0, va1, t + 2);
;         attn_tile(Kb0, vb0, q0, q1, negm, m, o0, o1, lacc, t == 0, wsf, r32, hi);
;         AT_STORE(kb0, kb1, vb0_, vb1_, 1);
;         __syncthreads();
;         if (t + 3 < NT) AT_LOAD(kb0, kb1, vb0_, vb1_, t + 3);
;         attn_tile(Kb0 + AT_KB, vb0 + AT_VB, q0, q1, negm, m, o0, o1, lacc, false, wsf, r32, hi);
;         if (t + 2 < NT) AT_STORE(ka0, ka1, va0, va1, 0);
;     }
;     ...
;     float lam, omli;
;     { float s1 = 0.f, s2 = 0.f;
;       for (int i = 0; i < 32; ++i) { s1 += a.lam_q1[l * 32 + i] * a.lam_k1[l * 32 + i]; s2 += a.lam_q2[l * 32 + i] * a.lam_k2[l * 32 + i]; }
;       const float li = 0.8f - 0.6f * expf(-0.3f * (float)l); lam = expf(s1) - expf(s2) + li; omli = 1.f - li; }
;     LAS float* stg = (LAS float*)(lds + AT_ST) + wq * 2048;
;     if (comp == 1) {
; #pragma unroll
;         for (int r = 0; r < 16; ++r) { const int qr = crow(r, hi); const float il = lam * __builtin_amdgcn_rcpf(lacc[r]); stg[qr * 64 + r32] = o0[r] * il; stg[qr * 64 + 32 + r32] = o1[r] * il; }
;     }
;     __syncthreads();
;     if (comp == 0) {
; #pragma unroll
;         for (int r = 0; r < 16; ++r) { const int qr = crow(r, hi); const float il = __builtin_amdgcn_rcpf(lacc[r]); o0[r] = o0[r] * il - stg[qr * 64 + r32]; o1[r] = o1[r] * il - stg[qr * 64 + 32 + r32]; }
;         asm volatile("s_waitcnt lgkmcnt(0)" ::: "memory");
; #pragma unroll
;         for (int r = 0; r < 16; ++r) { const int qr = crow(r, hi); stg[qr * 64 + r32] = o0[r]; stg[qr * 64 + 32 + r32] = o1[r]; }
;         asm volatile("s_waitcnt lgkmcnt(0)" ::: "memory");
;         const int ch = lane & 7;
;         float gsub[8];
; #pragma unroll
;         for (int i = 0; i < 8; ++i) gsub[i] = a.subln_g[l * 64 + ch * 8 + i] * omli;
.Lat_ndg5:
	ds_read_b128 v[48:51], v144 offset:0
	ds_read_b128 v[52:55], v145 offset:0
	ds_read_b128 v[56:59], v144 offset:4096
	ds_read_b128 v[60:63], v145 offset:4096
	v_mfma_f32_32x32x16_bf16 v[80:95], v[162:165], v[192:195], v[80:95]
	v_mfma_f32_32x32x16_bf16 v[200:215], v[162:165], v[196:199], v[200:215]
	s_add_u32 s33, s33, 1
	s_cmp_lt_u32 s33, 22
	s_cbranch_scc1 .Lat_loop
	v_add_f32_e32 v132, v128, v129
	v_mov_b32_e32 v133, v132
	s_nop 1
	v_permlane32_swap_b32_e32 v132, v133
	v_add_f32_e32 v135, v132, v133
	v_add_f32_e32 v132, v130, v131
	v_mov_b32_e32 v133, v132
	s_nop 1
	v_permlane32_swap_b32_e32 v132, v133
	v_add_f32_e32 v130, v132, v133
	s_nop 7
	s_waitcnt lgkmcnt(0)
	ds_write_b32 v148, v135
	s_waitcnt lgkmcnt(0)
	ds_read_b128 v[32:35], v147 offset:0
	ds_read_b128 v[36:39], v147 offset:32
	ds_read_b128 v[40:43], v147 offset:64
	ds_read_b128 v[44:47], v147 offset:96
	s_waitcnt lgkmcnt(0)
	s_mov_b32 s93, 0
	s_waitcnt vmcnt(0)
	v_or_b32_e32 v132, s58, v228
	v_mov_b32_e32 v133, 0
	v_lshl_add_u64 v[132:133], v[132:133], 2, s[78:79]
	global_load_dwordx4 v[100:103], v[132:133], off offset:16
	global_load_dwordx4 v[96:99], v[132:133], off
	s_setprio 0
	s_branch .LBB0_459

; #define LAS __attribute__((address_space(3)))
; __device__ __forceinline__ float sum8(float v) { v += dppmov<0xB1>(v); v += dppmov<0x4E>(v); v += dppmov<0x141>(v); return v; }
; __device__ __forceinline__ u32x4 pk8(const float (&v)[8]) { u32x4 w; w.x = pk2(v[0], v[1]); w.y = pk2(v[2], v[3]); w.z = pk2(v[4], v[5]); w.w = pk2(v[6], v[7]); return w; }
; __device__ __forceinline__ int crow(int r, int hi) { return (r & 3) + 8 * (r >> 2) + 4 * hi; }
; template <int VAR>
; __device__ __forceinline__ void attn_unit(const Args& a, int l, int b, int h, int qrow0  , bool ctxu, const bf16* Z, bf16* Y, LAS unsigned char* lds) {
;     ...
;     if (comp == 0) {
; #pragma unroll
;         for (int r = 0; r < 16; ++r) { const int qr = crow(r, hi); const float il = __builtin_amdgcn_rcpf(lacc[r]); o0[r] = o0[r] * il - stg[qr * 64 + r32]; o1[r] = o1[r] * il - stg[qr * 64 + 32 + r32]; }
;         asm volatile("s_waitcnt lgkmcnt(0)" ::: "memory");
; #pragma unroll
;         for (int r = 0; r < 16; ++r) { const int qr = crow(r, hi); stg[qr * 64 + r32] = o0[r]; stg[qr * 64 + 32 + r32] = o1[r]; }
;         asm volatile("s_waitcnt lgkmcnt(0)" ::: "memory");
;         const int ch = lane & 7;
;         float gsub[8];
; #pragma unroll
;         for (int i = 0; i < 8; ++i) gsub[i] = a.subln_g[l * 64 + ch * 8 + i] * omli;
; #pragma unroll
;         for (int i = 0; i < 4; ++i) { const int row = i * 8 + (lane >> 3);
;             const f32x4 x0 = *(const LAS f32x4*)(stg + row * 64 + ch * 8), x1 = *(const LAS f32x4*)(stg + row * 64 + ch * 8 + 4);
;             float ss = (x0.x * x0.x + x0.y * x0.y) + (x0.z * x0.z + x0.w * x0.w) + (x1.x * x1.x + x1.y * x1.y) + (x1.z * x1.z + x1.w * x1.w);
;             ss = sum8(ss);
;             const float rs = rsqrtf(ss * (1.f / 64.f) + 1e-6f);
;             float o[8] = {x0.x * rs * gsub[0], x0.y * rs * gsub[1], x0.z * rs * gsub[2], x0.w * rs * gsub[3], x1.x * rs * gsub[4], x1.y * rs * gsub[5], x1.z * rs * gsub[6], x1.w * rs * gsub[7]};
;             *(u32x4*)(Y + (size_t)(qrow0 + wq * 32 + row) * DM + 256 + h * 64 + ch * 8) = pk8(o); }
.LBB0_461:
	s_cmpk_gt_u32 s29, 0xff
	s_waitcnt lgkmcnt(0)
	s_barrier
	s_cbranch_scc1 .Lat_afterA
	v_add_u32_e32 v33, 0x800, v52
	v_add_u32_e32 v35, 0x1000, v52
	v_add_u32_e32 v36, 0x1800, v52
	ds_read2_b32 v[168:169], v52 offset1:32
	ds_read2_b32 v[170:171], v52 offset0:64 offset1:96
	ds_read2_b32 v[172:173], v52 offset0:128 offset1:160
	ds_read2_b32 v[174:175], v52 offset0:192 offset1:224
	ds_read2_b32 v[176:177], v33 offset1:32
	ds_read2_b32 v[178:179], v33 offset0:64 offset1:96
	ds_read2_b32 v[180:181], v33 offset0:128 offset1:160
	ds_read2_b32 v[182:183], v33 offset0:192 offset1:224
	ds_read2_b32 v[184:185], v35 offset1:32
	ds_read2_b32 v[186:187], v35 offset0:64 offset1:96
	ds_read2_b32 v[188:189], v35 offset0:128 offset1:160
	ds_read2_b32 v[190:191], v35 offset0:192 offset1:224
	v_readlane_b32 s76, v252, 43
	v_or_b32_e32 v216, s58, v228
	v_readlane_b32 s78, v252, 45
	v_readlane_b32 s79, v252, 46
	s_lshl_b32 s72, s28, 1
	v_readlane_b32 s77, v252, 44
	v_readlane_b32 s80, v252, 47
	v_readlane_b32 s81, v252, 48
	v_readlane_b32 s82, v252, 49
	v_readlane_b32 s83, v252, 50
	v_readlane_b32 s84, v252, 51
	v_readlane_b32 s85, v252, 52
	v_readlane_b32 s86, v252, 53
	v_readlane_b32 s87, v252, 54
	v_readlane_b32 s88, v252, 55
	v_readlane_b32 s89, v252, 56
	v_readlane_b32 s90, v252, 57
	v_readlane_b32 s91, v252, 58
	s_waitcnt lgkmcnt(8)
	v_fma_f32 v34, v0, v68, -v168
	v_fma_f32 v16, v16, v68, -v169
	v_fma_f32 v32, v1, v67, -v170
	v_fma_f32 v17, v17, v67, -v171
	v_fma_f32 v2, v2, v66, -v172
	v_fma_f32 v18, v18, v66, -v173
	v_fma_f32 v3, v3, v65, -v174
	v_fma_f32 v19, v19, v65, -v175
	ds_read2_b32 v[192:193], v36 offset1:32
	ds_read2_b32 v[194:195], v36 offset0:64 offset1:96
	ds_read2_b32 v[196:197], v36 offset0:128 offset1:160
	ds_read2_b32 v[198:199], v36 offset0:192 offset1:224
	s_waitcnt lgkmcnt(8)
	v_fma_f32 v4, v4, v64, -v176
	v_fma_f32 v20, v20, v64, -v177
	v_fma_f32 v5, v5, v63, -v178
	v_fma_f32 v21, v21, v63, -v179
	v_fma_f32 v6, v6, v62, -v180
	v_fma_f32 v22, v22, v62, -v181
	v_fma_f32 v7, v7, v61, -v182
	v_fma_f32 v23, v23, v61, -v183
	s_waitcnt lgkmcnt(4)
	v_fma_f32 v8, v8, v60, -v184
	v_fma_f32 v24, v24, v60, -v185
	v_fma_f32 v9, v9, v59, -v186
	v_fma_f32 v25, v25, v59, -v187
	v_fma_f32 v10, v10, v58, -v188
	v_fma_f32 v26, v26, v58, -v189
	v_fma_f32 v11, v11, v57, -v190
	v_fma_f32 v27, v27, v57, -v191
	s_waitcnt lgkmcnt(0)
	v_fma_f32 v12, v12, v56, -v192
	v_fma_f32 v28, v28, v56, -v193
	v_fma_f32 v13, v13, v55, -v194
	v_fma_f32 v29, v29, v55, -v195
	v_fma_f32 v14, v14, v54, -v196
	v_fma_f32 v30, v30, v54, -v197
	v_fma_f32 v0, v15, v53, -v198
	v_fma_f32 v1, v31, v53, -v199
	ds_write2_b32 v52, v34, v16 offset1:32
	ds_write2_b32 v52, v32, v17 offset0:64 offset1:96
	ds_write2_b32 v52, v2, v18 offset0:128 offset1:160
	ds_write2_b32 v52, v3, v19 offset0:192 offset1:224
	ds_write2_b32 v33, v4, v20 offset1:32
	ds_write2_b32 v33, v5, v21 offset0:64 offset1:96
	ds_write2_b32 v33, v6, v22 offset0:128 offset1:160
	ds_write2_b32 v33, v7, v23 offset0:192 offset1:224
	ds_write2_b32 v35, v8, v24 offset1:32
	ds_write2_b32 v35, v9, v25 offset0:64 offset1:96
	ds_write2_b32 v35, v10, v26 offset0:128 offset1:160
	ds_write2_b32 v35, v11, v27 offset0:192 offset1:224
	ds_write2_b32 v36, v12, v28 offset1:32
	ds_write2_b32 v36, v13, v29 offset0:64 offset1:96
	ds_write2_b32 v36, v14, v30 offset0:128 offset1:160
	ds_write2_b32 v36, v0, v1 offset0:192 offset1:224
	s_waitcnt lgkmcnt(0)
	v_lshrrev_b32_e32 v32, 3, v227
	v_lshl_add_u32 v33, v228, 2, s9
	v_lshl_add_u32 v0, v32, 8, v33
	ds_read_b128 v[8:11], v0
	ds_read_b128 v[16:19], v0 offset:16
	v_lshlrev_b32_e32 v216, 1, v228
	s_waitcnt lgkmcnt(1)
	v_pk_mul_f32 v[0:1], v[10:11], v[10:11]
	v_pk_mul_f32 v[2:3], v[8:9], v[8:9]
	v_mov_b32_e32 v227, v8
	v_pk_mov_b32 v[20:21], v[2:3], v[0:1] op_sel:[1,0]
	v_mov_b32_e32 v3, v1
	v_pk_add_f32 v[0:1], v[20:21], v[2:3]
	s_waitcnt lgkmcnt(0)
	v_pk_mul_f32 v[2:3], v[18:19], v[18:19]
	v_pk_mul_f32 v[20:21], v[16:17], v[16:17]
	v_mov_b32_e32 v22, v2
	v_mov_b32_e32 v23, v20
	v_mov_b32_e32 v20, v3
	v_pk_add_f32 v[2:3], v[22:23], v[20:21]
	v_add_f32_e32 v0, v0, v1
	v_add_f32_e32 v0, v0, v3
	v_add_f32_e32 v0, v2, v0
	s_waitcnt vmcnt(0)
	v_mov_b32_e32 v20, v96
	v_add_f32_dpp v0, v0, v0 quad_perm:[1,0,3,2] row_mask:0xf bank_mask:0xf bound_ctrl:1
	s_nop 1
	v_add_f32_dpp v0, v0, v0 quad_perm:[2,3,0,1] row_mask:0xf bank_mask:0xf bound_ctrl:1
	s_nop 1
	v_add_f32_dpp v0, v0, v0 row_half_mirror row_mask:0xf bank_mask:0xf bound_ctrl:1
	v_fmamk_f32 v0, v0, 0x3c800000, v218
	v_cmp_gt_f32_e32 vcc, s66, v0
	v_mul_f32_e32 v1, 0x4b800000, v0
	s_nop 0
	v_cndmask_b32_e32 v0, v0, v1, vcc
	v_rsq_f32_e32 v0, v0
	s_nop 0
	v_mul_f32_e32 v1, 0x45800000, v0
	v_cndmask_b32_e32 v21, v0, v1, vcc
	v_pk_mul_f32 v[0:1], v[226:227], v[20:21]
	v_mov_b32_e32 v227, v9
	v_mov_b32_e32 v20, v97
	v_pk_mul_f32 v[2:3], v[226:227], v[20:21]
	v_mov_b32_e32 v227, v10
	v_mov_b32_e32 v20, v98
	v_pk_mul_f32 v[4:5], v[226:227], v[20:21]
	v_mov_b32_e32 v227, v11
	v_mov_b32_e32 v20, v99
	v_pk_mul_f32 v[6:7], v[226:227], v[20:21]
	v_mov_b32_e32 v227, v16
	v_mov_b32_e32 v20, v100
	v_pk_mul_f32 v[8:9], v[226:227], v[20:21]
	v_mov_b32_e32 v227, v17
	v_mov_b32_e32 v20, v101
	v_pk_mul_f32 v[10:11], v[226:227], v[20:21]
	v_mov_b32_e32 v227, v18
	v_mov_b32_e32 v20, v102
	v_pk_mul_f32 v[12:13], v[226:227], v[20:21]
	v_mov_b32_e32 v227, v19
	v_mov_b32_e32 v20, v103
	v_pk_mul_f32 v[14:15], v[226:227], v[20:21]
	v_or_b32_e32 v20, s60, v32
	v_ashrrev_i32_e32 v21, 31, v20
	v_lshlrev_b64 v[20:21], 11, v[20:21]
	v_lshl_add_u64 v[20:21], s[20:21], 0, v[20:21]
	v_mul_f32_e32 v1, v0, v1
	v_lshl_add_u64 v[20:21], v[20:21], 0, s[72:73]
	v_mul_f32_e32 v3, v2, v3
	v_cvt_pk_bf16_f32 v16, v1, v3
	v_lshl_add_u64 v[20:21], v[20:21], 0, v[216:217]
	v_or_b32_e32 v1, 8, v32
	v_mul_f32_e32 v5, v4, v5
	v_mul_f32_e32 v7, v6, v7
	v_mul_f32_e32 v9, v8, v9
	v_mul_f32_e32 v11, v10, v11
	v_mul_f32_e32 v13, v12, v13
	v_mul_f32_e32 v15, v14, v15
	v_cvt_pk_bf16_f32 v17, v5, v7
	v_cvt_pk_bf16_f32 v18, v9, v11
	v_cvt_pk_bf16_f32 v19, v13, v15
	global_store_dwordx4 v[20:21], v[16:19], off offset:512
	v_lshl_add_u32 v3, v1, 8, v33
	ds_read_b128 v[16:19], v3
	ds_read_b128 v[20:23], v3 offset:16
	s_waitcnt lgkmcnt(1)
; #define LAS __attribute__((address_space(3)))
; __device__ __forceinline__ float sum8(float v) { v += dppmov<0xB1>(v); v += dppmov<0x4E>(v); v += dppmov<0x141>(v); return v; }
; __device__ __forceinline__ u32x4 pk8(const float (&v)[8]) { u32x4 w; w.x = pk2(v[0], v[1]); w.y = pk2(v[2], v[3]); w.z = pk2(v[4], v[5]); w.w = pk2(v[6], v[7]); return w; }
; template <int VAR>
; __device__ __forceinline__ void attn_unit(const Args& a, int l, int b, int h, int qrow0  , bool ctxu, const bf16* Z, bf16* Y, LAS unsigned char* lds) {
;     ...
;         for (int i = 0; i < 4; ++i) { const int row = i * 8 + (lane >> 3);
;             const f32x4 x0 = *(const LAS f32x4*)(stg + row * 64 + ch * 8), x1 = *(const LAS f32x4*)(stg + row * 64 + ch * 8 + 4);
;             float ss = (x0.x * x0.x + x0.y * x0.y) + (x0.z * x0.z + x0.w * x0.w) + (x1.x * x1.x + x1.y * x1.y) + (x1.z * x1.z + x1.w * x1.w);
;             ss = sum8(ss);
;             const float rs = rsqrtf(ss * (1.f / 64.f) + 1e-6f);
;             float o[8] = {x0.x * rs * gsub[0], x0.y * rs * gsub[1], x0.z * rs * gsub[2], x0.w * rs * gsub[3], x1.x * rs * gsub[4], x1.y * rs * gsub[5], x1.z * rs * gsub[6], x1.w * rs * gsub[7]};
;             *(u32x4*)(Y + (size_t)(qrow0 + wq * 32 + row) * DM + 256 + h * 64 + ch * 8) = pk8(o); }
	v_pk_mul_f32 v[24:25], v[18:19], v[18:19]
	v_pk_mul_f32 v[26:27], v[16:17], v[16:17]
	s_nop 0
	v_pk_mov_b32 v[28:29], v[26:27], v[24:25] op_sel:[1,0]
	v_mov_b32_e32 v27, v25
	v_pk_add_f32 v[24:25], v[28:29], v[26:27]
	s_waitcnt lgkmcnt(0)
	v_pk_mul_f32 v[26:27], v[22:23], v[22:23]
	v_pk_mul_f32 v[28:29], v[20:21], v[20:21]
	v_mov_b32_e32 v30, v26
	v_mov_b32_e32 v31, v28
	v_mov_b32_e32 v28, v27
	v_pk_add_f32 v[26:27], v[30:31], v[28:29]
	v_add_f32_e32 v3, v24, v25
	v_add_f32_e32 v3, v3, v27
	v_add_f32_e32 v3, v26, v3
	s_nop 1
	v_add_f32_dpp v3, v3, v3 quad_perm:[1,0,3,2] row_mask:0xf bank_mask:0xf bound_ctrl:1
	s_nop 1
	v_add_f32_dpp v3, v3, v3 quad_perm:[2,3,0,1] row_mask:0xf bank_mask:0xf bound_ctrl:1
	s_nop 1
	v_add_f32_dpp v3, v3, v3 row_half_mirror row_mask:0xf bank_mask:0xf bound_ctrl:1
	v_fmamk_f32 v3, v3, 0x3c800000, v218
	v_cmp_gt_f32_e32 vcc, s66, v3
	v_mul_f32_e32 v5, 0x4b800000, v3
	s_nop 0
	v_cndmask_b32_e32 v3, v3, v5, vcc
	v_rsq_f32_e32 v3, v3
	s_nop 0
	v_mul_f32_e32 v5, 0x45800000, v3
	v_cndmask_b32_e32 v3, v3, v5, vcc
	v_mul_f32_e32 v13, v20, v3
	v_or_b32_e32 v20, s60, v1
	v_mul_f32_e32 v15, v21, v3
	v_ashrrev_i32_e32 v21, 31, v20
	v_lshlrev_b64 v[20:21], 11, v[20:21]
	v_lshl_add_u64 v[20:21], s[20:21], 0, v[20:21]
	v_mul_f32_e32 v5, v16, v3
	v_mul_f32_e32 v7, v17, v3
	v_mul_f32_e32 v9, v18, v3
	v_mul_f32_e32 v11, v19, v3
	v_mul_f32_e32 v16, v22, v3
	v_mul_f32_e32 v3, v23, v3
	v_lshl_add_u64 v[20:21], v[20:21], 0, s[72:73]
	v_mul_f32_e32 v19, v12, v16
	v_mul_f32_e32 v3, v14, v3
	v_lshl_add_u64 v[20:21], v[20:21], 0, v[216:217]
	v_or_b32_e32 v1, 16, v32
	v_mul_f32_e32 v5, v0, v5
	v_mul_f32_e32 v7, v2, v7
	v_mul_f32_e32 v9, v4, v9
	v_mul_f32_e32 v11, v6, v11
	v_mul_f32_e32 v13, v8, v13
	v_mul_f32_e32 v15, v10, v15
	v_cvt_pk_bf16_f32 v16, v5, v7
	v_cvt_pk_bf16_f32 v17, v9, v11
	v_cvt_pk_bf16_f32 v18, v13, v15
	v_cvt_pk_bf16_f32 v19, v19, v3
	global_store_dwordx4 v[20:21], v[16:19], off offset:512
	v_lshl_add_u32 v3, v1, 8, v33
	ds_read_b128 v[16:19], v3
	ds_read_b128 v[20:23], v3 offset:16
	s_waitcnt lgkmcnt(1)
	v_pk_mul_f32 v[24:25], v[18:19], v[18:19]
	v_pk_mul_f32 v[26:27], v[16:17], v[16:17]
	s_nop 0
	v_pk_mov_b32 v[28:29], v[26:27], v[24:25] op_sel:[1,0]
	v_mov_b32_e32 v27, v25
	v_pk_add_f32 v[24:25], v[28:29], v[26:27]
	s_waitcnt lgkmcnt(0)
	v_pk_mul_f32 v[26:27], v[22:23], v[22:23]
	v_pk_mul_f32 v[28:29], v[20:21], v[20:21]
	v_mov_b32_e32 v30, v26
	v_mov_b32_e32 v31, v28
	v_mov_b32_e32 v28, v27
	v_pk_add_f32 v[26:27], v[30:31], v[28:29]
	v_add_f32_e32 v3, v24, v25
	v_add_f32_e32 v3, v3, v27
	v_add_f32_e32 v3, v26, v3
	s_nop 1
	v_add_f32_dpp v3, v3, v3 quad_perm:[1,0,3,2] row_mask:0xf bank_mask:0xf bound_ctrl:1
	s_nop 1
	v_add_f32_dpp v3, v3, v3 quad_perm:[2,3,0,1] row_mask:0xf bank_mask:0xf bound_ctrl:1
	s_nop 1
	v_add_f32_dpp v3, v3, v3 row_half_mirror row_mask:0xf bank_mask:0xf bound_ctrl:1
	v_fmamk_f32 v3, v3, 0x3c800000, v218
	v_cmp_gt_f32_e32 vcc, s66, v3
	v_mul_f32_e32 v5, 0x4b800000, v3
	s_nop 0
	v_cndmask_b32_e32 v3, v3, v5, vcc
	v_rsq_f32_e32 v3, v3
	s_nop 0
	v_mul_f32_e32 v5, 0x45800000, v3
	v_cndmask_b32_e32 v3, v3, v5, vcc
	v_mul_f32_e32 v13, v20, v3
	v_or_b32_e32 v20, s60, v1
	v_mul_f32_e32 v15, v21, v3
	v_ashrrev_i32_e32 v21, 31, v20
	v_lshlrev_b64 v[20:21], 11, v[20:21]
	v_mul_f32_e32 v5, v16, v3
	v_lshl_add_u64 v[20:21], s[20:21], 0, v[20:21]
	v_mul_f32_e32 v5, v0, v5
	v_mul_f32_e32 v7, v17, v3
	v_mul_f32_e32 v16, v22, v3
	v_lshl_add_u64 v[20:21], v[20:21], 0, s[72:73]
	v_mul_f32_e32 v7, v2, v7
	v_mul_f32_e32 v9, v18, v3
	v_mul_f32_e32 v11, v19, v3
	v_mul_f32_e32 v19, v12, v16
	v_mul_f32_e32 v3, v23, v3
	v_cvt_pk_bf16_f32 v16, v5, v7
	v_lshl_add_u64 v[20:21], v[20:21], 0, v[216:217]
	v_or_b32_e32 v5, 24, v32
	v_mul_f32_e32 v9, v4, v9
	v_mul_f32_e32 v11, v6, v11
	v_mul_f32_e32 v13, v8, v13
	v_mul_f32_e32 v15, v10, v15
	v_mul_f32_e32 v3, v14, v3
	v_cvt_pk_bf16_f32 v17, v9, v11
	v_cvt_pk_bf16_f32 v18, v13, v15
	v_cvt_pk_bf16_f32 v19, v19, v3
	global_store_dwordx4 v[20:21], v[16:19], off offset:512
	v_lshl_add_u32 v1, v5, 8, v33
	ds_read_b128 v[16:19], v1
	ds_read_b128 v[20:23], v1 offset:16
	s_waitcnt lgkmcnt(1)
	v_pk_mul_f32 v[24:25], v[18:19], v[18:19]
	v_pk_mul_f32 v[26:27], v[16:17], v[16:17]
	s_nop 0
	v_pk_mov_b32 v[28:29], v[26:27], v[24:25] op_sel:[1,0]
	v_mov_b32_e32 v27, v25
	v_pk_add_f32 v[24:25], v[28:29], v[26:27]
	s_waitcnt lgkmcnt(0)
	v_pk_mul_f32 v[26:27], v[22:23], v[22:23]
	v_pk_mul_f32 v[28:29], v[20:21], v[20:21]
	v_mov_b32_e32 v30, v26
	v_mov_b32_e32 v31, v28
	v_mov_b32_e32 v28, v27
	v_pk_add_f32 v[26:27], v[30:31], v[28:29]
	v_add_f32_e32 v1, v24, v25
	v_add_f32_e32 v1, v1, v27
	v_add_f32_e32 v1, v26, v1
	s_nop 1
	v_add_f32_dpp v1, v1, v1 quad_perm:[1,0,3,2] row_mask:0xf bank_mask:0xf bound_ctrl:1
	s_nop 1
	v_add_f32_dpp v1, v1, v1 quad_perm:[2,3,0,1] row_mask:0xf bank_mask:0xf bound_ctrl:1
	s_nop 1
	v_add_f32_dpp v1, v1, v1 row_half_mirror row_mask:0xf bank_mask:0xf bound_ctrl:1
	v_fmamk_f32 v1, v1, 0x3c800000, v218
	v_cmp_gt_f32_e32 vcc, s66, v1
	v_mul_f32_e32 v3, 0x4b800000, v1
	s_nop 0
	v_cndmask_b32_e32 v1, v1, v3, vcc
	v_rsq_f32_e32 v1, v1
	s_nop 0
	v_mul_f32_e32 v3, 0x45800000, v1
	v_cndmask_b32_e32 v1, v1, v3, vcc
	v_mul_f32_e32 v3, v16, v1
	v_mul_f32_e32 v0, v0, v3
	v_mul_f32_e32 v3, v17, v1
	v_mul_f32_e32 v2, v2, v3
	v_mul_f32_e32 v3, v18, v1
	v_mul_f32_e32 v3, v4, v3
	v_mul_f32_e32 v4, v19, v1
	v_mul_f32_e32 v4, v6, v4
	v_mul_f32_e32 v6, v20, v1
	v_mul_f32_e32 v6, v8, v6
	v_mul_f32_e32 v7, v21, v1
	v_mul_f32_e32 v8, v22, v1
	v_mul_f32_e32 v1, v23, v1
	v_mul_f32_e32 v9, v14, v1
	v_cvt_pk_bf16_f32 v0, v0, v2
	v_cvt_pk_bf16_f32 v1, v3, v4
	v_or_b32_e32 v4, s60, v5
	v_ashrrev_i32_e32 v5, 31, v4
	v_lshlrev_b64 v[4:5], 11, v[4:5]
	v_lshl_add_u64 v[4:5], s[20:21], 0, v[4:5]
	v_lshl_add_u64 v[4:5], v[4:5], 0, s[72:73]
	v_lshl_add_u64 v[4:5], v[4:5], 0, v[216:217]
	v_mul_f32_e32 v7, v10, v7
	v_mul_f32_e32 v8, v12, v8
	v_cvt_pk_bf16_f32 v2, v6, v7
	v_cvt_pk_bf16_f32 v3, v8, v9
	global_store_dwordx4 v[4:5], v[0:3], off offset:512
	s_branch .Lat_afterA
